# s7.5 re-spacing in the SwiGLU epilogues: 18 adjacent independent silu chain pairs interleaved instruction by instruction (second chain's temporary renamed to a dead MFMA-operand register), dropping th
# baseline (speedup 1.0000x reference)
; __device__ __forceinline__ unsigned cvt_pk_bf16(float lo, float hi) { unsigned r; asm volatile("v_cvt_pk_bf16_f32 %0, %1, %2" : "=v"(r) : "v"(lo), "v"(hi)); return r; }
;     __device__ __forceinline__ static float sg(float g, float uu) { return g * __builtin_amdgcn_rcpf(1.0f + __builtin_amdgcn_exp2f(-1.4426950408889634f * g)) * uu; }
;     __device__ __forceinline__ void operator()(const f32x4 (&acc)[2][2][4][2], const Unit& u, int wr, int wc, int fr, int fq) const {
;         const int row0 = u.pm * BM + wr * 64 + fr, col0 = u.pn * BM + wc * 32 + 8 * fq;
;         float rsv[2][4];
; #pragma unroll
;         for (int ai = 0; ai < 2; ++ai) {
; #pragma unroll
;             for (int m = 0; m < 4; ++m) rsv[ai][m] = row_rstd16_coop(ssq, row0 + ai * HALF + m * 16, fq, 1.0f / 1024.0f);
;         }
; #pragma unroll
;         for (int ai = 0; ai < 2; ++ai)
; #pragma unroll
;             for (int m = 0; m < 4; ++m) {
;                 const int row = row0 + ai * HALF + m * 16;
;                 const float rs = rsv[ai][m];
;                 bf16_t* rowp = H + (size_t)row * ldh + (col0 >> 1);
; #pragma unroll
;                 for (int bj = 0; bj < 2; ++bj) {
;                     const f32x4 v0 = acc[ai][bj][m][0] * rs, v1 = acc[ai][bj][m][1] * rs;
;                     u32x2 w; w.x = cvt_pk_bf16(sg(v0[0], v0[1]), sg(v0[2], v0[3])); w.y = cvt_pk_bf16(sg(v1[0], v1[1]), sg(v1[2], v1[3]));
;                     *(u32x2*)(rowp + bj * (HALF / 2)) = w;
;                 }
;             }
.Lmy_rs_join_0:
	v_mul_f32_e32 v122, v122, v131
	v_mul_f32_e32 v122, v123, v122
	v_mul_f32_e32 v123, 0xbfb8aa3b, v124
	v_exp_f32_e32 v123, v123
	v_pk_mul_f32 v[14:15], v[14:15], v[130:131] op_sel_hi:[1,0]
	v_pk_mul_f32 v[16:17], v[16:17], v[130:131] op_sel_hi:[1,0]
	v_pk_mul_f32 v[10:11], v[10:11], v[130:131] op_sel_hi:[1,0]
	v_add_f32_e32 v123, 1.0, v123
	v_rcp_f32_e32 v123, v123
	v_pk_mul_f32 v[12:13], v[12:13], v[130:131] op_sel_hi:[1,0]
	v_pk_mul_f32 v[6:7], v[6:7], v[130:131] op_sel_hi:[1,0]
	v_pk_mul_f32 v[8:9], v[8:9], v[130:131] op_sel_hi:[1,0]
	v_mul_f32_e32 v123, v124, v123
	v_mul_f32_e32 v123, v125, v123
	v_cvt_pk_bf16_f32 v122, v122, v123
	v_mul_f32_e32 v123, 0xbfb8aa3b, v126
	v_exp_f32_e32 v123, v123
	v_mul_f32_e32 v124, 0xbfb8aa3b, v128
	v_exp_f32_e32 v124, v124
	v_pk_mul_f32 v[2:3], v[2:3], v[130:131] op_sel_hi:[1,0]
	v_add_f32_e32 v123, 1.0, v123
	v_rcp_f32_e32 v123, v123
	v_add_f32_e32 v124, 1.0, v124
	v_rcp_f32_e32 v124, v124
	v_pk_mul_f32 v[4:5], v[4:5], v[130:131] op_sel_hi:[1,0]
	v_mul_f32_e32 v123, v126, v123
	v_mul_f32_e32 v123, v127, v123
	v_mul_f32_e32 v124, v128, v124
	v_mul_f32_e32 v124, v129, v124
	v_cvt_pk_bf16_f32 v123, v123, v124
	s_waitcnt vmcnt(0)
	global_store_dwordx2 v[178:179], v[122:123], off
	v_mul_f32_e32 v122, 0xbfb8aa3b, v118
	v_mul_f32_e32 v216, 0xbfb8aa3b, v120
	v_exp_f32_e32 v122, v122
	v_exp_f32_e32 v216, v216
	v_add_f32_e32 v122, 1.0, v122
	v_add_f32_e32 v216, 1.0, v216
	v_rcp_f32_e32 v122, v122
	v_rcp_f32_e32 v216, v216
	v_mul_f32_e32 v118, v118, v122
	v_mul_f32_e32 v216, v120, v216
	v_mul_f32_e32 v118, v119, v118
	v_mul_f32_e32 v119, v121, v216
	v_cvt_pk_bf16_f32 v118, v118, v119
	v_mul_f32_e32 v119, 0xbfb8aa3b, v114
	v_exp_f32_e32 v119, v119
	s_nop 0
	v_add_f32_e32 v119, 1.0, v119
	v_rcp_f32_e32 v119, v119
	s_nop 0
	v_mul_f32_e32 v114, v114, v119
	v_mul_f32_e32 v114, v115, v114
	v_mul_f32_e32 v115, 0xbfb8aa3b, v116
	v_exp_f32_e32 v115, v115
	s_nop 0
	v_add_f32_e32 v115, 1.0, v115
	v_rcp_f32_e32 v115, v115
	s_nop 0
	v_mul_f32_e32 v115, v116, v115
	v_mul_f32_e32 v116, 0xbfb8aa3b, v110
	v_exp_f32_e32 v116, v116
	v_mul_f32_e32 v115, v117, v115
	v_cvt_pk_bf16_f32 v119, v114, v115
	global_store_dwordx2 v[178:179], v[118:119], off offset:128
	v_add_f32_e32 v116, 1.0, v116
	v_rcp_f32_e32 v116, v116
	v_mad_i64_i32 v[114:115], s[30:31], v174, s96, v[132:133]
	v_lshl_add_u64 v[114:115], v[114:115], 0, v[156:157]
	v_mul_f32_e32 v110, v110, v116
	v_mul_f32_e32 v110, v111, v110
	v_mul_f32_e32 v111, 0xbfb8aa3b, v112
	v_exp_f32_e32 v111, v111
	s_nop 0
	v_add_f32_e32 v111, 1.0, v111
	v_rcp_f32_e32 v111, v111
	s_nop 0
	v_mul_f32_e32 v111, v112, v111
	v_mul_f32_e32 v111, v113, v111
	v_cvt_pk_bf16_f32 v110, v110, v111
	v_mul_f32_e32 v111, 0xbfb8aa3b, v106
	v_mul_f32_e32 v216, 0xbfb8aa3b, v108
	v_exp_f32_e32 v111, v111
	v_exp_f32_e32 v216, v216
	v_add_f32_e32 v111, 1.0, v111
	v_add_f32_e32 v216, 1.0, v216
	v_rcp_f32_e32 v111, v111
	v_rcp_f32_e32 v216, v216
	v_mul_f32_e32 v106, v106, v111
	v_mul_f32_e32 v216, v108, v216
	v_mul_f32_e32 v106, v107, v106
	v_mul_f32_e32 v107, v109, v216
	v_cvt_pk_bf16_f32 v111, v106, v107
	v_mul_f32_e32 v106, 0xbfb8aa3b, v102
	v_exp_f32_e32 v106, v106
	global_store_dwordx2 v[114:115], v[110:111], off
	v_add_f32_e32 v106, 1.0, v106
	v_rcp_f32_e32 v106, v106
	s_nop 0
	v_mul_f32_e32 v102, v102, v106
	v_mul_f32_e32 v102, v103, v102
	v_mul_f32_e32 v103, 0xbfb8aa3b, v104
	v_exp_f32_e32 v103, v103
	s_nop 0
	v_add_f32_e32 v103, 1.0, v103
	v_rcp_f32_e32 v103, v103
	s_nop 0
	v_mul_f32_e32 v103, v104, v103
	v_mul_f32_e32 v103, v105, v103
	v_cvt_pk_bf16_f32 v102, v102, v103
	v_mul_f32_e32 v103, 0xbfb8aa3b, v98
	v_exp_f32_e32 v103, v103
	s_nop 0
	v_add_f32_e32 v103, 1.0, v103
	v_rcp_f32_e32 v103, v103
	s_nop 0
	v_mul_f32_e32 v98, v98, v103
	v_mul_f32_e32 v98, v99, v98
	v_mul_f32_e32 v99, 0xbfb8aa3b, v100
	v_exp_f32_e32 v99, v99
	s_nop 0
	v_add_f32_e32 v99, 1.0, v99
	v_rcp_f32_e32 v99, v99
	s_nop 0
	v_mul_f32_e32 v99, v100, v99
	v_mul_f32_e32 v100, 0xbfb8aa3b, v94
	v_exp_f32_e32 v100, v100
	v_mul_f32_e32 v99, v101, v99
	v_cvt_pk_bf16_f32 v103, v98, v99
	global_store_dwordx2 v[114:115], v[102:103], off offset:128
	v_add_f32_e32 v100, 1.0, v100
	v_rcp_f32_e32 v100, v100
	v_mad_i64_i32 v[98:99], s[30:31], v170, s96, v[132:133]
	v_lshl_add_u64 v[98:99], v[98:99], 0, v[156:157]
	v_mul_f32_e32 v94, v94, v100
	v_mul_f32_e32 v94, v95, v94
	v_mul_f32_e32 v95, 0xbfb8aa3b, v96
	v_exp_f32_e32 v95, v95
	s_nop 0
	v_add_f32_e32 v95, 1.0, v95
	v_rcp_f32_e32 v95, v95
	s_nop 0
	v_mul_f32_e32 v95, v96, v95
	v_mul_f32_e32 v95, v97, v95
	v_cvt_pk_bf16_f32 v94, v94, v95
	v_mul_f32_e32 v95, 0xbfb8aa3b, v90
	v_mul_f32_e32 v216, 0xbfb8aa3b, v92
	v_exp_f32_e32 v95, v95
	v_exp_f32_e32 v216, v216
	v_add_f32_e32 v95, 1.0, v95
	v_add_f32_e32 v216, 1.0, v216
	v_rcp_f32_e32 v95, v95
	v_rcp_f32_e32 v216, v216
	v_mul_f32_e32 v90, v90, v95
	v_mul_f32_e32 v216, v92, v216
	v_mul_f32_e32 v90, v91, v90
	v_mul_f32_e32 v91, v93, v216
	v_cvt_pk_bf16_f32 v95, v90, v91
	v_mul_f32_e32 v90, 0xbfb8aa3b, v86
	v_exp_f32_e32 v90, v90
	global_store_dwordx2 v[98:99], v[94:95], off
	v_add_f32_e32 v90, 1.0, v90
	v_rcp_f32_e32 v90, v90
	s_nop 0
	v_mul_f32_e32 v86, v86, v90
	v_mul_f32_e32 v86, v87, v86
	v_mul_f32_e32 v87, 0xbfb8aa3b, v88
	v_exp_f32_e32 v87, v87
	s_nop 0
	v_add_f32_e32 v87, 1.0, v87
	v_rcp_f32_e32 v87, v87
	s_nop 0
	v_mul_f32_e32 v87, v88, v87
	v_mul_f32_e32 v87, v89, v87
	v_cvt_pk_bf16_f32 v86, v86, v87
	v_mul_f32_e32 v87, 0xbfb8aa3b, v82
	v_exp_f32_e32 v87, v87
	s_nop 0
	v_add_f32_e32 v87, 1.0, v87
	v_rcp_f32_e32 v87, v87
	s_nop 0
	v_mul_f32_e32 v82, v82, v87
	v_mul_f32_e32 v82, v83, v82
	v_mul_f32_e32 v83, 0xbfb8aa3b, v84
; __device__ __forceinline__ unsigned cvt_pk_bf16(float lo, float hi) { unsigned r; asm volatile("v_cvt_pk_bf16_f32 %0, %1, %2" : "=v"(r) : "v"(lo), "v"(hi)); return r; }
;     __device__ __forceinline__ static float sg(float g, float uu) { return g * __builtin_amdgcn_rcpf(1.0f + __builtin_amdgcn_exp2f(-1.4426950408889634f * g)) * uu; }
;     __device__ __forceinline__ void operator()(const f32x4 (&acc)[2][2][4][2], const Unit& u, int wr, int wc, int fr, int fq) const {
;         const int row0 = u.pm * BM + wr * 64 + fr, col0 = u.pn * BM + wc * 32 + 8 * fq;
;         float rsv[2][4];
; #pragma unroll
;         for (int ai = 0; ai < 2; ++ai) {
; #pragma unroll
;             for (int m = 0; m < 4; ++m) rsv[ai][m] = row_rstd16_coop(ssq, row0 + ai * HALF + m * 16, fq, 1.0f / 1024.0f);
;         }
; #pragma unroll
;         for (int ai = 0; ai < 2; ++ai)
; #pragma unroll
;             for (int m = 0; m < 4; ++m) {
;                 const int row = row0 + ai * HALF + m * 16;
;                 const float rs = rsv[ai][m];
;                 bf16_t* rowp = H + (size_t)row * ldh + (col0 >> 1);
; #pragma unroll
;                 for (int bj = 0; bj < 2; ++bj) {
;                     const f32x4 v0 = acc[ai][bj][m][0] * rs, v1 = acc[ai][bj][m][1] * rs;
;                     u32x2 w; w.x = cvt_pk_bf16(sg(v0[0], v0[1]), sg(v0[2], v0[3])); w.y = cvt_pk_bf16(sg(v1[0], v1[1]), sg(v1[2], v1[3]));
;                     *(u32x2*)(rowp + bj * (HALF / 2)) = w;
;                 }
;             }
	v_exp_f32_e32 v83, v83
	s_nop 0
	v_add_f32_e32 v83, 1.0, v83
	v_rcp_f32_e32 v83, v83
	s_nop 0
	v_mul_f32_e32 v83, v84, v83
	v_mul_f32_e32 v84, 0xbfb8aa3b, v78
	v_exp_f32_e32 v84, v84
	v_mul_f32_e32 v83, v85, v83
	v_cvt_pk_bf16_f32 v87, v82, v83
	global_store_dwordx2 v[98:99], v[86:87], off offset:128
	v_add_f32_e32 v84, 1.0, v84
	v_rcp_f32_e32 v84, v84
	v_mad_i64_i32 v[82:83], s[30:31], v166, s96, v[132:133]
	v_lshl_add_u64 v[82:83], v[82:83], 0, v[156:157]
	v_mul_f32_e32 v78, v78, v84
	v_mul_f32_e32 v78, v79, v78
	v_mul_f32_e32 v79, 0xbfb8aa3b, v80
	v_exp_f32_e32 v79, v79
	s_nop 0
	v_add_f32_e32 v79, 1.0, v79
	v_rcp_f32_e32 v79, v79
	s_nop 0
	v_mul_f32_e32 v79, v80, v79
	v_mul_f32_e32 v79, v81, v79
	v_cvt_pk_bf16_f32 v78, v78, v79
	v_mul_f32_e32 v79, 0xbfb8aa3b, v74
	v_mul_f32_e32 v216, 0xbfb8aa3b, v76
	v_exp_f32_e32 v79, v79
	v_exp_f32_e32 v216, v216
	v_add_f32_e32 v79, 1.0, v79
	v_add_f32_e32 v216, 1.0, v216
	v_rcp_f32_e32 v79, v79
	v_rcp_f32_e32 v216, v216
	v_mul_f32_e32 v74, v74, v79
	v_mul_f32_e32 v216, v76, v216
	v_mul_f32_e32 v74, v75, v74
	v_mul_f32_e32 v75, v77, v216
	v_cvt_pk_bf16_f32 v79, v74, v75
	v_mul_f32_e32 v74, 0xbfb8aa3b, v70
	v_exp_f32_e32 v74, v74
	global_store_dwordx2 v[82:83], v[78:79], off
	v_add_f32_e32 v74, 1.0, v74
	v_rcp_f32_e32 v74, v74
	s_nop 0
	v_mul_f32_e32 v70, v70, v74
	v_mul_f32_e32 v70, v71, v70
	v_mul_f32_e32 v71, 0xbfb8aa3b, v72
	v_exp_f32_e32 v71, v71
	s_nop 0
	v_add_f32_e32 v71, 1.0, v71
	v_rcp_f32_e32 v71, v71
	s_nop 0
	v_mul_f32_e32 v71, v72, v71
	v_mul_f32_e32 v71, v73, v71
	v_cvt_pk_bf16_f32 v70, v70, v71
	v_mul_f32_e32 v71, 0xbfb8aa3b, v66
	v_exp_f32_e32 v71, v71
	s_nop 0
	v_add_f32_e32 v71, 1.0, v71
	v_rcp_f32_e32 v71, v71
	s_nop 0
	v_mul_f32_e32 v66, v66, v71
	v_mul_f32_e32 v66, v67, v66
	v_mul_f32_e32 v67, 0xbfb8aa3b, v68
	v_exp_f32_e32 v67, v67
	s_nop 0
	v_add_f32_e32 v67, 1.0, v67
	v_rcp_f32_e32 v67, v67
	s_nop 0
	v_mul_f32_e32 v67, v68, v67
	v_mul_f32_e32 v68, 0xbfb8aa3b, v62
	v_exp_f32_e32 v68, v68
	v_mul_f32_e32 v67, v69, v67
	v_cvt_pk_bf16_f32 v71, v66, v67
	global_store_dwordx2 v[82:83], v[70:71], off offset:128
	v_add_f32_e32 v68, 1.0, v68
	v_rcp_f32_e32 v68, v68
	v_mad_i64_i32 v[66:67], s[30:31], v162, s96, v[132:133]
	v_lshl_add_u64 v[66:67], v[66:67], 0, v[156:157]
	v_mul_f32_e32 v62, v62, v68
	v_mul_f32_e32 v62, v63, v62
	v_mul_f32_e32 v63, 0xbfb8aa3b, v64
	v_exp_f32_e32 v63, v63
	s_nop 0
	v_add_f32_e32 v63, 1.0, v63
	v_rcp_f32_e32 v63, v63
	s_nop 0
	v_mul_f32_e32 v63, v64, v63
	v_mul_f32_e32 v63, v65, v63
	v_cvt_pk_bf16_f32 v62, v62, v63
	v_mul_f32_e32 v63, 0xbfb8aa3b, v58
	v_mul_f32_e32 v216, 0xbfb8aa3b, v60
	v_exp_f32_e32 v63, v63
	v_exp_f32_e32 v216, v216
	v_add_f32_e32 v63, 1.0, v63
	v_add_f32_e32 v216, 1.0, v216
	v_rcp_f32_e32 v63, v63
	v_rcp_f32_e32 v216, v216
	v_mul_f32_e32 v58, v58, v63
	v_mul_f32_e32 v216, v60, v216
	v_mul_f32_e32 v58, v59, v58
	v_mul_f32_e32 v59, v61, v216
	v_cvt_pk_bf16_f32 v63, v58, v59
	v_mul_f32_e32 v58, 0xbfb8aa3b, v54
	v_exp_f32_e32 v58, v58
	global_store_dwordx2 v[66:67], v[62:63], off
	v_add_f32_e32 v58, 1.0, v58
	v_rcp_f32_e32 v58, v58
	s_nop 0
	v_mul_f32_e32 v54, v54, v58
	v_mul_f32_e32 v54, v55, v54
	v_mul_f32_e32 v55, 0xbfb8aa3b, v56
	v_exp_f32_e32 v55, v55
	s_nop 0
	v_add_f32_e32 v55, 1.0, v55
	v_rcp_f32_e32 v55, v55
	s_nop 0
	v_mul_f32_e32 v55, v56, v55
	v_mul_f32_e32 v55, v57, v55
	v_cvt_pk_bf16_f32 v54, v54, v55
	v_mul_f32_e32 v55, 0xbfb8aa3b, v50
	v_exp_f32_e32 v55, v55
	s_nop 0
	v_add_f32_e32 v55, 1.0, v55
	v_rcp_f32_e32 v55, v55
	s_nop 0
	v_mul_f32_e32 v50, v50, v55
	v_mul_f32_e32 v50, v51, v50
	v_mul_f32_e32 v51, 0xbfb8aa3b, v52
	v_exp_f32_e32 v51, v51
	s_nop 0
	v_add_f32_e32 v51, 1.0, v51
	v_rcp_f32_e32 v51, v51
	s_nop 0
	v_mul_f32_e32 v51, v52, v51
	v_mul_f32_e32 v52, 0xbfb8aa3b, v46
	v_exp_f32_e32 v52, v52
	v_mul_f32_e32 v51, v53, v51
	v_cvt_pk_bf16_f32 v55, v50, v51
	global_store_dwordx2 v[66:67], v[54:55], off offset:128
	v_add_f32_e32 v52, 1.0, v52
	v_rcp_f32_e32 v52, v52
	v_mad_i64_i32 v[50:51], s[30:31], v158, s96, v[132:133]
	v_lshl_add_u64 v[50:51], v[50:51], 0, v[156:157]
	v_mul_f32_e32 v46, v46, v52
	v_mul_f32_e32 v46, v47, v46
	v_mul_f32_e32 v47, 0xbfb8aa3b, v48
	v_exp_f32_e32 v47, v47
	s_nop 0
	v_add_f32_e32 v47, 1.0, v47
	v_rcp_f32_e32 v47, v47
	s_nop 0
	v_mul_f32_e32 v47, v48, v47
	v_mul_f32_e32 v47, v49, v47
	v_cvt_pk_bf16_f32 v46, v46, v47
	v_mul_f32_e32 v47, 0xbfb8aa3b, v42
	v_mul_f32_e32 v216, 0xbfb8aa3b, v44
	v_exp_f32_e32 v47, v47
	v_exp_f32_e32 v216, v216
	v_add_f32_e32 v47, 1.0, v47
	v_add_f32_e32 v216, 1.0, v216
	v_rcp_f32_e32 v47, v47
	v_rcp_f32_e32 v216, v216
	v_mul_f32_e32 v42, v42, v47
	v_mul_f32_e32 v216, v44, v216
	v_mul_f32_e32 v42, v43, v42
; __device__ __forceinline__ unsigned cvt_pk_bf16(float lo, float hi) { unsigned r; asm volatile("v_cvt_pk_bf16_f32 %0, %1, %2" : "=v"(r) : "v"(lo), "v"(hi)); return r; }
;     __device__ __forceinline__ static float sg(float g, float uu) { return g * __builtin_amdgcn_rcpf(1.0f + __builtin_amdgcn_exp2f(-1.4426950408889634f * g)) * uu; }
;     __device__ __forceinline__ void operator()(const f32x4 (&acc)[2][2][4][2], const Unit& u, int wr, int wc, int fr, int fq) const {
;         const int row0 = u.pm * BM + wr * 64 + fr, col0 = u.pn * BM + wc * 32 + 8 * fq;
;         float rsv[2][4];
; #pragma unroll
;         for (int ai = 0; ai < 2; ++ai) {
; #pragma unroll
;             for (int m = 0; m < 4; ++m) rsv[ai][m] = row_rstd16_coop(ssq, row0 + ai * HALF + m * 16, fq, 1.0f / 1024.0f);
;         }
; #pragma unroll
;         for (int ai = 0; ai < 2; ++ai)
; #pragma unroll
;             for (int m = 0; m < 4; ++m) {
;                 const int row = row0 + ai * HALF + m * 16;
;                 const float rs = rsv[ai][m];
;                 bf16_t* rowp = H + (size_t)row * ldh + (col0 >> 1);
; #pragma unroll
;                 for (int bj = 0; bj < 2; ++bj) {
;                     const f32x4 v0 = acc[ai][bj][m][0] * rs, v1 = acc[ai][bj][m][1] * rs;
;                     u32x2 w; w.x = cvt_pk_bf16(sg(v0[0], v0[1]), sg(v0[2], v0[3])); w.y = cvt_pk_bf16(sg(v1[0], v1[1]), sg(v1[2], v1[3]));
;                     *(u32x2*)(rowp + bj * (HALF / 2)) = w;
;                 }
;             }
	v_mul_f32_e32 v43, v45, v216
	v_cvt_pk_bf16_f32 v47, v42, v43
	v_mul_f32_e32 v42, 0xbfb8aa3b, v38
	v_exp_f32_e32 v42, v42
	global_store_dwordx2 v[50:51], v[46:47], off
	v_add_f32_e32 v42, 1.0, v42
	v_rcp_f32_e32 v42, v42
	s_nop 0
	v_mul_f32_e32 v38, v38, v42
	v_mul_f32_e32 v38, v39, v38
	v_mul_f32_e32 v39, 0xbfb8aa3b, v40
	v_exp_f32_e32 v39, v39
	s_nop 0
	v_add_f32_e32 v39, 1.0, v39
	v_rcp_f32_e32 v39, v39
	s_nop 0
	v_mul_f32_e32 v39, v40, v39
	v_mul_f32_e32 v39, v41, v39
	v_cvt_pk_bf16_f32 v38, v38, v39
	v_mul_f32_e32 v39, 0xbfb8aa3b, v34
	v_exp_f32_e32 v39, v39
	s_nop 0
	v_add_f32_e32 v39, 1.0, v39
	v_rcp_f32_e32 v39, v39
	s_nop 0
	v_mul_f32_e32 v34, v34, v39
	v_mul_f32_e32 v34, v35, v34
	v_mul_f32_e32 v35, 0xbfb8aa3b, v36
	v_exp_f32_e32 v35, v35
	s_nop 0
	v_add_f32_e32 v35, 1.0, v35
	v_rcp_f32_e32 v35, v35
	s_nop 0
	v_mul_f32_e32 v35, v36, v35
	v_mul_f32_e32 v36, 0xbfb8aa3b, v30
	v_exp_f32_e32 v36, v36
	v_mul_f32_e32 v35, v37, v35
	v_cvt_pk_bf16_f32 v39, v34, v35
	global_store_dwordx2 v[50:51], v[38:39], off offset:128
	v_add_f32_e32 v36, 1.0, v36
	v_rcp_f32_e32 v36, v36
	v_mad_i64_i32 v[34:35], s[30:31], v152, s96, v[132:133]
	v_lshl_add_u64 v[34:35], v[34:35], 0, v[156:157]
	v_mul_f32_e32 v30, v30, v36
	v_mul_f32_e32 v30, v31, v30
	v_mul_f32_e32 v31, 0xbfb8aa3b, v32
	v_exp_f32_e32 v31, v31
	s_nop 0
	v_add_f32_e32 v31, 1.0, v31
	v_rcp_f32_e32 v31, v31
	s_nop 0
	v_mul_f32_e32 v31, v32, v31
	v_mul_f32_e32 v31, v33, v31
	v_cvt_pk_bf16_f32 v30, v30, v31
	v_mul_f32_e32 v31, 0xbfb8aa3b, v26
	v_mul_f32_e32 v216, 0xbfb8aa3b, v28
	v_exp_f32_e32 v31, v31
	v_exp_f32_e32 v216, v216
	v_add_f32_e32 v31, 1.0, v31
	v_add_f32_e32 v216, 1.0, v216
	v_rcp_f32_e32 v31, v31
	v_rcp_f32_e32 v216, v216
	v_mul_f32_e32 v26, v26, v31
	v_mul_f32_e32 v216, v28, v216
	v_mul_f32_e32 v26, v27, v26
	v_mul_f32_e32 v27, v29, v216
	v_cvt_pk_bf16_f32 v31, v26, v27
	v_mul_f32_e32 v26, 0xbfb8aa3b, v22
	v_exp_f32_e32 v26, v26
	global_store_dwordx2 v[34:35], v[30:31], off
	v_add_f32_e32 v26, 1.0, v26
	v_rcp_f32_e32 v26, v26
	s_nop 0
	v_mul_f32_e32 v22, v22, v26
	v_mul_f32_e32 v22, v23, v22
	v_mul_f32_e32 v23, 0xbfb8aa3b, v24
	v_exp_f32_e32 v23, v23
	s_nop 0
	v_add_f32_e32 v23, 1.0, v23
	v_rcp_f32_e32 v23, v23
	s_nop 0
	v_mul_f32_e32 v23, v24, v23
	v_mul_f32_e32 v23, v25, v23
	v_cvt_pk_bf16_f32 v22, v22, v23
	v_mul_f32_e32 v23, 0xbfb8aa3b, v18
	v_exp_f32_e32 v23, v23
	s_nop 0
	v_add_f32_e32 v23, 1.0, v23
	v_rcp_f32_e32 v23, v23
	s_nop 0
	v_mul_f32_e32 v18, v18, v23
	v_mul_f32_e32 v18, v19, v18
	v_mul_f32_e32 v19, 0xbfb8aa3b, v20
	v_exp_f32_e32 v19, v19
	s_nop 0
	v_add_f32_e32 v19, 1.0, v19
	v_rcp_f32_e32 v19, v19
	s_nop 0
	v_mul_f32_e32 v19, v20, v19
	v_mul_f32_e32 v20, 0xbfb8aa3b, v14
	v_exp_f32_e32 v20, v20
	v_mul_f32_e32 v19, v21, v19
	v_cvt_pk_bf16_f32 v23, v18, v19
	global_store_dwordx2 v[34:35], v[22:23], off offset:128
	v_add_f32_e32 v20, 1.0, v20
	v_rcp_f32_e32 v20, v20
	v_mad_i64_i32 v[18:19], s[30:31], v148, s96, v[132:133]
	v_lshl_add_u64 v[18:19], v[18:19], 0, v[156:157]
	v_mul_f32_e32 v14, v14, v20
	v_mul_f32_e32 v14, v15, v14
	v_mul_f32_e32 v15, 0xbfb8aa3b, v16
	v_exp_f32_e32 v15, v15
	s_mov_b64 s[30:31], -1
	v_add_f32_e32 v15, 1.0, v15
	v_rcp_f32_e32 v15, v15
	s_nop 0
	v_mul_f32_e32 v15, v16, v15
	v_mul_f32_e32 v15, v17, v15
	v_cvt_pk_bf16_f32 v14, v14, v15
	v_mul_f32_e32 v15, 0xbfb8aa3b, v10
	v_mul_f32_e32 v216, 0xbfb8aa3b, v12
	v_exp_f32_e32 v15, v15
	v_exp_f32_e32 v216, v216
	v_add_f32_e32 v15, 1.0, v15
	v_add_f32_e32 v216, 1.0, v216
	v_rcp_f32_e32 v15, v15
	v_rcp_f32_e32 v216, v216
	v_mul_f32_e32 v10, v10, v15
	v_mul_f32_e32 v216, v12, v216
	v_mul_f32_e32 v10, v11, v10
	v_mul_f32_e32 v11, v13, v216
	v_cvt_pk_bf16_f32 v15, v10, v11
	v_mul_f32_e32 v10, 0xbfb8aa3b, v6
	v_exp_f32_e32 v10, v10
	global_store_dwordx2 v[18:19], v[14:15], off
	v_add_f32_e32 v10, 1.0, v10
	v_rcp_f32_e32 v10, v10
	s_nop 0
	v_mul_f32_e32 v6, v6, v10
	v_mul_f32_e32 v6, v7, v6
	v_mul_f32_e32 v7, 0xbfb8aa3b, v8
	v_exp_f32_e32 v7, v7
	s_nop 0
	v_add_f32_e32 v7, 1.0, v7
	v_rcp_f32_e32 v7, v7
	s_nop 0
	v_mul_f32_e32 v7, v8, v7
	v_mul_f32_e32 v7, v9, v7
	v_cvt_pk_bf16_f32 v6, v6, v7
	v_mul_f32_e32 v7, 0xbfb8aa3b, v2
	v_mul_f32_e32 v216, 0xbfb8aa3b, v4
	v_exp_f32_e32 v7, v7
	v_exp_f32_e32 v216, v216
	v_add_f32_e32 v7, 1.0, v7
	v_add_f32_e32 v216, 1.0, v216
	v_rcp_f32_e32 v7, v7
	v_rcp_f32_e32 v216, v216
	v_mul_f32_e32 v2, v2, v7
	v_mul_f32_e32 v216, v4, v216
	v_mul_f32_e32 v2, v3, v2
	v_mul_f32_e32 v3, v5, v216
	v_cvt_pk_bf16_f32 v7, v2, v3
	global_store_dwordx2 v[18:19], v[6:7], off offset:128
	s_cbranch_vccnz .LBB0_3152
	s_andn2_b64 vcc, exec, s[20:21]
	s_cbranch_vccnz .LBB0_3151
	s_barrier
	s_branch .LBB0_3151

; __device__ __forceinline__ unsigned cvt_pk_bf16(float lo, float hi) { unsigned r; asm volatile("v_cvt_pk_bf16_f32 %0, %1, %2" : "=v"(r) : "v"(lo), "v"(hi)); return r; }
;     __device__ __forceinline__ static float sg(float g, float uu) { return g * __builtin_amdgcn_rcpf(1.0f + __builtin_amdgcn_exp2f(-1.4426950408889634f * g)) * uu; }
;     __device__ __forceinline__ void operator()(const f32x4 (&acc)[2][2][4][2], const Unit& u, int wr, int wc, int fr, int fq) const {
;         const int row0 = u.pm * BM + wr * 64 + fr, col0 = u.pn * BM + wc * 32 + 8 * fq;
;         float rsv[2][4];
; #pragma unroll
;         for (int ai = 0; ai < 2; ++ai) {
; #pragma unroll
;             for (int m = 0; m < 4; ++m) rsv[ai][m] = row_rstd16_coop(ssq, row0 + ai * HALF + m * 16, fq, 1.0f / 1024.0f);
;         }
; #pragma unroll
;         for (int ai = 0; ai < 2; ++ai)
; #pragma unroll
;             for (int m = 0; m < 4; ++m) {
;                 const int row = row0 + ai * HALF + m * 16;
;                 const float rs = rsv[ai][m];
;                 bf16_t* rowp = H + (size_t)row * ldh + (col0 >> 1);
; #pragma unroll
;                 for (int bj = 0; bj < 2; ++bj) {
;                     const f32x4 v0 = acc[ai][bj][m][0] * rs, v1 = acc[ai][bj][m][1] * rs;
;                     u32x2 w; w.x = cvt_pk_bf16(sg(v0[0], v0[1]), sg(v0[2], v0[3])); w.y = cvt_pk_bf16(sg(v1[0], v1[1]), sg(v1[2], v1[3]));
;                     *(u32x2*)(rowp + bj * (HALF / 2)) = w;
;                 }
;             }
.Lmy_rs_join_3:
	v_mul_f32_e32 v122, v122, v131
	v_mul_f32_e32 v122, v123, v122
	v_mul_f32_e32 v123, 0xbfb8aa3b, v124
	v_exp_f32_e32 v123, v123
	v_pk_mul_f32 v[14:15], v[14:15], v[130:131] op_sel_hi:[1,0]
	v_pk_mul_f32 v[16:17], v[16:17], v[130:131] op_sel_hi:[1,0]
	v_pk_mul_f32 v[10:11], v[10:11], v[130:131] op_sel_hi:[1,0]
	v_add_f32_e32 v123, 1.0, v123
	v_rcp_f32_e32 v123, v123
	v_pk_mul_f32 v[12:13], v[12:13], v[130:131] op_sel_hi:[1,0]
	v_pk_mul_f32 v[6:7], v[6:7], v[130:131] op_sel_hi:[1,0]
	v_pk_mul_f32 v[8:9], v[8:9], v[130:131] op_sel_hi:[1,0]
	v_mul_f32_e32 v123, v124, v123
	v_mul_f32_e32 v123, v125, v123
	v_cvt_pk_bf16_f32 v122, v122, v123
	v_mul_f32_e32 v123, 0xbfb8aa3b, v126
	v_exp_f32_e32 v123, v123
	v_mul_f32_e32 v124, 0xbfb8aa3b, v128
	v_exp_f32_e32 v124, v124
	v_pk_mul_f32 v[2:3], v[2:3], v[130:131] op_sel_hi:[1,0]
	v_add_f32_e32 v123, 1.0, v123
	v_rcp_f32_e32 v123, v123
	v_add_f32_e32 v124, 1.0, v124
	v_rcp_f32_e32 v124, v124
	v_pk_mul_f32 v[4:5], v[4:5], v[130:131] op_sel_hi:[1,0]
	v_mul_f32_e32 v123, v126, v123
	v_mul_f32_e32 v123, v127, v123
	v_mul_f32_e32 v124, v128, v124
	v_mul_f32_e32 v124, v129, v124
	v_cvt_pk_bf16_f32 v123, v123, v124
	s_waitcnt vmcnt(0)
	global_store_dwordx2 v[178:179], v[122:123], off
	v_mul_f32_e32 v122, 0xbfb8aa3b, v118
	v_mul_f32_e32 v216, 0xbfb8aa3b, v120
	v_exp_f32_e32 v122, v122
	v_exp_f32_e32 v216, v216
	v_add_f32_e32 v122, 1.0, v122
	v_add_f32_e32 v216, 1.0, v216
	v_rcp_f32_e32 v122, v122
	v_rcp_f32_e32 v216, v216
	v_mul_f32_e32 v118, v118, v122
	v_mul_f32_e32 v216, v120, v216
	v_mul_f32_e32 v118, v119, v118
	v_mul_f32_e32 v119, v121, v216
	v_cvt_pk_bf16_f32 v118, v118, v119
	v_mul_f32_e32 v119, 0xbfb8aa3b, v114
	v_exp_f32_e32 v119, v119
	s_nop 0
	v_add_f32_e32 v119, 1.0, v119
	v_rcp_f32_e32 v119, v119
	s_nop 0
	v_mul_f32_e32 v114, v114, v119
	v_mul_f32_e32 v114, v115, v114
	v_mul_f32_e32 v115, 0xbfb8aa3b, v116
	v_exp_f32_e32 v115, v115
	s_nop 0
	v_add_f32_e32 v115, 1.0, v115
	v_rcp_f32_e32 v115, v115
	s_nop 0
	v_mul_f32_e32 v115, v116, v115
	v_mul_f32_e32 v116, 0xbfb8aa3b, v110
	v_exp_f32_e32 v116, v116
	v_mul_f32_e32 v115, v117, v115
	v_cvt_pk_bf16_f32 v119, v114, v115
	global_store_dwordx2 v[178:179], v[118:119], off offset:128
	v_add_f32_e32 v116, 1.0, v116
	v_rcp_f32_e32 v116, v116
	v_mad_i64_i32 v[114:115], s[24:25], v174, s96, v[132:133]
	v_lshl_add_u64 v[114:115], v[114:115], 0, v[156:157]
	v_mul_f32_e32 v110, v110, v116
	v_mul_f32_e32 v110, v111, v110
	v_mul_f32_e32 v111, 0xbfb8aa3b, v112
	v_exp_f32_e32 v111, v111
	s_nop 0
	v_add_f32_e32 v111, 1.0, v111
	v_rcp_f32_e32 v111, v111
	s_nop 0
	v_mul_f32_e32 v111, v112, v111
	v_mul_f32_e32 v111, v113, v111
	v_cvt_pk_bf16_f32 v110, v110, v111
	v_mul_f32_e32 v111, 0xbfb8aa3b, v106
	v_mul_f32_e32 v216, 0xbfb8aa3b, v108
	v_exp_f32_e32 v111, v111
	v_exp_f32_e32 v216, v216
	v_add_f32_e32 v111, 1.0, v111
	v_add_f32_e32 v216, 1.0, v216
	v_rcp_f32_e32 v111, v111
	v_rcp_f32_e32 v216, v216
	v_mul_f32_e32 v106, v106, v111
	v_mul_f32_e32 v216, v108, v216
	v_mul_f32_e32 v106, v107, v106
	v_mul_f32_e32 v107, v109, v216
	v_cvt_pk_bf16_f32 v111, v106, v107
	v_mul_f32_e32 v106, 0xbfb8aa3b, v102
	v_exp_f32_e32 v106, v106
	global_store_dwordx2 v[114:115], v[110:111], off
	v_add_f32_e32 v106, 1.0, v106
	v_rcp_f32_e32 v106, v106
	s_nop 0
	v_mul_f32_e32 v102, v102, v106
	v_mul_f32_e32 v102, v103, v102
	v_mul_f32_e32 v103, 0xbfb8aa3b, v104
	v_exp_f32_e32 v103, v103
	s_nop 0
	v_add_f32_e32 v103, 1.0, v103
	v_rcp_f32_e32 v103, v103
	s_nop 0
	v_mul_f32_e32 v103, v104, v103
	v_mul_f32_e32 v103, v105, v103
	v_cvt_pk_bf16_f32 v102, v102, v103
	v_mul_f32_e32 v103, 0xbfb8aa3b, v98
	v_exp_f32_e32 v103, v103
	s_nop 0
	v_add_f32_e32 v103, 1.0, v103
	v_rcp_f32_e32 v103, v103
	s_nop 0
	v_mul_f32_e32 v98, v98, v103
	v_mul_f32_e32 v98, v99, v98
	v_mul_f32_e32 v99, 0xbfb8aa3b, v100
	v_exp_f32_e32 v99, v99
	s_nop 0
	v_add_f32_e32 v99, 1.0, v99
	v_rcp_f32_e32 v99, v99
	s_nop 0
	v_mul_f32_e32 v99, v100, v99
	v_mul_f32_e32 v100, 0xbfb8aa3b, v94
	v_exp_f32_e32 v100, v100
	v_mul_f32_e32 v99, v101, v99
	v_cvt_pk_bf16_f32 v103, v98, v99
	global_store_dwordx2 v[114:115], v[102:103], off offset:128
	v_add_f32_e32 v100, 1.0, v100
	v_rcp_f32_e32 v100, v100
	v_mad_i64_i32 v[98:99], s[24:25], v170, s96, v[132:133]
	v_lshl_add_u64 v[98:99], v[98:99], 0, v[156:157]
	v_mul_f32_e32 v94, v94, v100
	v_mul_f32_e32 v94, v95, v94
	v_mul_f32_e32 v95, 0xbfb8aa3b, v96
	v_exp_f32_e32 v95, v95
	s_nop 0
	v_add_f32_e32 v95, 1.0, v95
	v_rcp_f32_e32 v95, v95
	s_nop 0
	v_mul_f32_e32 v95, v96, v95
	v_mul_f32_e32 v95, v97, v95
	v_cvt_pk_bf16_f32 v94, v94, v95
	v_mul_f32_e32 v95, 0xbfb8aa3b, v90
	v_mul_f32_e32 v216, 0xbfb8aa3b, v92
	v_exp_f32_e32 v95, v95
	v_exp_f32_e32 v216, v216
	v_add_f32_e32 v95, 1.0, v95
	v_add_f32_e32 v216, 1.0, v216
	v_rcp_f32_e32 v95, v95
	v_rcp_f32_e32 v216, v216
	v_mul_f32_e32 v90, v90, v95
	v_mul_f32_e32 v216, v92, v216
	v_mul_f32_e32 v90, v91, v90
	v_mul_f32_e32 v91, v93, v216
	v_cvt_pk_bf16_f32 v95, v90, v91
	v_mul_f32_e32 v90, 0xbfb8aa3b, v86
	v_exp_f32_e32 v90, v90
	global_store_dwordx2 v[98:99], v[94:95], off
	v_add_f32_e32 v90, 1.0, v90
	v_rcp_f32_e32 v90, v90
	s_nop 0
	v_mul_f32_e32 v86, v86, v90
	v_mul_f32_e32 v86, v87, v86
	v_mul_f32_e32 v87, 0xbfb8aa3b, v88
	v_exp_f32_e32 v87, v87
	s_nop 0
	v_add_f32_e32 v87, 1.0, v87
	v_rcp_f32_e32 v87, v87
	s_nop 0
	v_mul_f32_e32 v87, v88, v87
	v_mul_f32_e32 v87, v89, v87
	v_cvt_pk_bf16_f32 v86, v86, v87
	v_mul_f32_e32 v87, 0xbfb8aa3b, v82
	v_exp_f32_e32 v87, v87
	s_nop 0
	v_add_f32_e32 v87, 1.0, v87
	v_rcp_f32_e32 v87, v87
	s_nop 0
	v_mul_f32_e32 v82, v82, v87
	v_mul_f32_e32 v82, v83, v82
	v_mul_f32_e32 v83, 0xbfb8aa3b, v84
; __device__ __forceinline__ unsigned cvt_pk_bf16(float lo, float hi) { unsigned r; asm volatile("v_cvt_pk_bf16_f32 %0, %1, %2" : "=v"(r) : "v"(lo), "v"(hi)); return r; }
;     __device__ __forceinline__ static float sg(float g, float uu) { return g * __builtin_amdgcn_rcpf(1.0f + __builtin_amdgcn_exp2f(-1.4426950408889634f * g)) * uu; }
;     __device__ __forceinline__ void operator()(const f32x4 (&acc)[2][2][4][2], const Unit& u, int wr, int wc, int fr, int fq) const {
;         const int row0 = u.pm * BM + wr * 64 + fr, col0 = u.pn * BM + wc * 32 + 8 * fq;
;         float rsv[2][4];
; #pragma unroll
;         for (int ai = 0; ai < 2; ++ai) {
; #pragma unroll
;             for (int m = 0; m < 4; ++m) rsv[ai][m] = row_rstd16_coop(ssq, row0 + ai * HALF + m * 16, fq, 1.0f / 1024.0f);
;         }
; #pragma unroll
;         for (int ai = 0; ai < 2; ++ai)
; #pragma unroll
;             for (int m = 0; m < 4; ++m) {
;                 const int row = row0 + ai * HALF + m * 16;
;                 const float rs = rsv[ai][m];
;                 bf16_t* rowp = H + (size_t)row * ldh + (col0 >> 1);
; #pragma unroll
;                 for (int bj = 0; bj < 2; ++bj) {
;                     const f32x4 v0 = acc[ai][bj][m][0] * rs, v1 = acc[ai][bj][m][1] * rs;
;                     u32x2 w; w.x = cvt_pk_bf16(sg(v0[0], v0[1]), sg(v0[2], v0[3])); w.y = cvt_pk_bf16(sg(v1[0], v1[1]), sg(v1[2], v1[3]));
;                     *(u32x2*)(rowp + bj * (HALF / 2)) = w;
;                 }
;             }
	v_exp_f32_e32 v83, v83
	s_nop 0
	v_add_f32_e32 v83, 1.0, v83
	v_rcp_f32_e32 v83, v83
	s_nop 0
	v_mul_f32_e32 v83, v84, v83
	v_mul_f32_e32 v84, 0xbfb8aa3b, v78
	v_exp_f32_e32 v84, v84
	v_mul_f32_e32 v83, v85, v83
	v_cvt_pk_bf16_f32 v87, v82, v83
	global_store_dwordx2 v[98:99], v[86:87], off offset:128
	v_add_f32_e32 v84, 1.0, v84
	v_rcp_f32_e32 v84, v84
	v_mad_i64_i32 v[82:83], s[24:25], v166, s96, v[132:133]
	v_lshl_add_u64 v[82:83], v[82:83], 0, v[156:157]
	v_mul_f32_e32 v78, v78, v84
	v_mul_f32_e32 v78, v79, v78
	v_mul_f32_e32 v79, 0xbfb8aa3b, v80
	v_exp_f32_e32 v79, v79
	s_nop 0
	v_add_f32_e32 v79, 1.0, v79
	v_rcp_f32_e32 v79, v79
	s_nop 0
	v_mul_f32_e32 v79, v80, v79
	v_mul_f32_e32 v79, v81, v79
	v_cvt_pk_bf16_f32 v78, v78, v79
	v_mul_f32_e32 v79, 0xbfb8aa3b, v74
	v_mul_f32_e32 v216, 0xbfb8aa3b, v76
	v_exp_f32_e32 v79, v79
	v_exp_f32_e32 v216, v216
	v_add_f32_e32 v79, 1.0, v79
	v_add_f32_e32 v216, 1.0, v216
	v_rcp_f32_e32 v79, v79
	v_rcp_f32_e32 v216, v216
	v_mul_f32_e32 v74, v74, v79
	v_mul_f32_e32 v216, v76, v216
	v_mul_f32_e32 v74, v75, v74
	v_mul_f32_e32 v75, v77, v216
	v_cvt_pk_bf16_f32 v79, v74, v75
	v_mul_f32_e32 v74, 0xbfb8aa3b, v70
	v_exp_f32_e32 v74, v74
	global_store_dwordx2 v[82:83], v[78:79], off
	v_add_f32_e32 v74, 1.0, v74
	v_rcp_f32_e32 v74, v74
	s_nop 0
	v_mul_f32_e32 v70, v70, v74
	v_mul_f32_e32 v70, v71, v70
	v_mul_f32_e32 v71, 0xbfb8aa3b, v72
	v_exp_f32_e32 v71, v71
	s_nop 0
	v_add_f32_e32 v71, 1.0, v71
	v_rcp_f32_e32 v71, v71
	s_nop 0
	v_mul_f32_e32 v71, v72, v71
	v_mul_f32_e32 v71, v73, v71
	v_cvt_pk_bf16_f32 v70, v70, v71
	v_mul_f32_e32 v71, 0xbfb8aa3b, v66
	v_exp_f32_e32 v71, v71
	s_nop 0
	v_add_f32_e32 v71, 1.0, v71
	v_rcp_f32_e32 v71, v71
	s_nop 0
	v_mul_f32_e32 v66, v66, v71
	v_mul_f32_e32 v66, v67, v66
	v_mul_f32_e32 v67, 0xbfb8aa3b, v68
	v_exp_f32_e32 v67, v67
	s_nop 0
	v_add_f32_e32 v67, 1.0, v67
	v_rcp_f32_e32 v67, v67
	s_nop 0
	v_mul_f32_e32 v67, v68, v67
	v_mul_f32_e32 v68, 0xbfb8aa3b, v62
	v_exp_f32_e32 v68, v68
	v_mul_f32_e32 v67, v69, v67
	v_cvt_pk_bf16_f32 v71, v66, v67
	global_store_dwordx2 v[82:83], v[70:71], off offset:128
	v_add_f32_e32 v68, 1.0, v68
	v_rcp_f32_e32 v68, v68
	v_mad_i64_i32 v[66:67], s[24:25], v162, s96, v[132:133]
	v_lshl_add_u64 v[66:67], v[66:67], 0, v[156:157]
	v_mul_f32_e32 v62, v62, v68
	v_mul_f32_e32 v62, v63, v62
	v_mul_f32_e32 v63, 0xbfb8aa3b, v64
	v_exp_f32_e32 v63, v63
	s_nop 0
	v_add_f32_e32 v63, 1.0, v63
	v_rcp_f32_e32 v63, v63
	s_nop 0
	v_mul_f32_e32 v63, v64, v63
	v_mul_f32_e32 v63, v65, v63
	v_cvt_pk_bf16_f32 v62, v62, v63
	v_mul_f32_e32 v63, 0xbfb8aa3b, v58
	v_mul_f32_e32 v216, 0xbfb8aa3b, v60
	v_exp_f32_e32 v63, v63
	v_exp_f32_e32 v216, v216
	v_add_f32_e32 v63, 1.0, v63
	v_add_f32_e32 v216, 1.0, v216
	v_rcp_f32_e32 v63, v63
	v_rcp_f32_e32 v216, v216
	v_mul_f32_e32 v58, v58, v63
	v_mul_f32_e32 v216, v60, v216
	v_mul_f32_e32 v58, v59, v58
	v_mul_f32_e32 v59, v61, v216
	v_cvt_pk_bf16_f32 v63, v58, v59
	v_mul_f32_e32 v58, 0xbfb8aa3b, v54
	v_exp_f32_e32 v58, v58
	global_store_dwordx2 v[66:67], v[62:63], off
	v_add_f32_e32 v58, 1.0, v58
	v_rcp_f32_e32 v58, v58
	s_nop 0
	v_mul_f32_e32 v54, v54, v58
	v_mul_f32_e32 v54, v55, v54
	v_mul_f32_e32 v55, 0xbfb8aa3b, v56
	v_exp_f32_e32 v55, v55
	s_nop 0
	v_add_f32_e32 v55, 1.0, v55
	v_rcp_f32_e32 v55, v55
	s_nop 0
	v_mul_f32_e32 v55, v56, v55
	v_mul_f32_e32 v55, v57, v55
	v_cvt_pk_bf16_f32 v54, v54, v55
	v_mul_f32_e32 v55, 0xbfb8aa3b, v50
	v_exp_f32_e32 v55, v55
	s_nop 0
	v_add_f32_e32 v55, 1.0, v55
	v_rcp_f32_e32 v55, v55
	s_nop 0
	v_mul_f32_e32 v50, v50, v55
	v_mul_f32_e32 v50, v51, v50
	v_mul_f32_e32 v51, 0xbfb8aa3b, v52
	v_exp_f32_e32 v51, v51
	s_nop 0
	v_add_f32_e32 v51, 1.0, v51
	v_rcp_f32_e32 v51, v51
	s_nop 0
	v_mul_f32_e32 v51, v52, v51
	v_mul_f32_e32 v52, 0xbfb8aa3b, v46
	v_exp_f32_e32 v52, v52
	v_mul_f32_e32 v51, v53, v51
	v_cvt_pk_bf16_f32 v55, v50, v51
	global_store_dwordx2 v[66:67], v[54:55], off offset:128
	v_add_f32_e32 v52, 1.0, v52
	v_rcp_f32_e32 v52, v52
	v_mad_i64_i32 v[50:51], s[24:25], v158, s96, v[132:133]
	v_lshl_add_u64 v[50:51], v[50:51], 0, v[156:157]
	v_mul_f32_e32 v46, v46, v52
	v_mul_f32_e32 v46, v47, v46
	v_mul_f32_e32 v47, 0xbfb8aa3b, v48
	v_exp_f32_e32 v47, v47
	s_nop 0
	v_add_f32_e32 v47, 1.0, v47
	v_rcp_f32_e32 v47, v47
	s_nop 0
	v_mul_f32_e32 v47, v48, v47
	v_mul_f32_e32 v47, v49, v47
	v_cvt_pk_bf16_f32 v46, v46, v47
	v_mul_f32_e32 v47, 0xbfb8aa3b, v42
	v_mul_f32_e32 v216, 0xbfb8aa3b, v44
	v_exp_f32_e32 v47, v47
	v_exp_f32_e32 v216, v216
	v_add_f32_e32 v47, 1.0, v47
	v_add_f32_e32 v216, 1.0, v216
	v_rcp_f32_e32 v47, v47
	v_rcp_f32_e32 v216, v216
	v_mul_f32_e32 v42, v42, v47
	v_mul_f32_e32 v216, v44, v216
	v_mul_f32_e32 v42, v43, v42
; __device__ __forceinline__ unsigned cvt_pk_bf16(float lo, float hi) { unsigned r; asm volatile("v_cvt_pk_bf16_f32 %0, %1, %2" : "=v"(r) : "v"(lo), "v"(hi)); return r; }
;     __device__ __forceinline__ static float sg(float g, float uu) { return g * __builtin_amdgcn_rcpf(1.0f + __builtin_amdgcn_exp2f(-1.4426950408889634f * g)) * uu; }
;     __device__ __forceinline__ void operator()(const f32x4 (&acc)[2][2][4][2], const Unit& u, int wr, int wc, int fr, int fq) const {
;         const int row0 = u.pm * BM + wr * 64 + fr, col0 = u.pn * BM + wc * 32 + 8 * fq;
;         float rsv[2][4];
; #pragma unroll
;         for (int ai = 0; ai < 2; ++ai) {
; #pragma unroll
;             for (int m = 0; m < 4; ++m) rsv[ai][m] = row_rstd16_coop(ssq, row0 + ai * HALF + m * 16, fq, 1.0f / 1024.0f);
;         }
; #pragma unroll
;         for (int ai = 0; ai < 2; ++ai)
; #pragma unroll
;             for (int m = 0; m < 4; ++m) {
;                 const int row = row0 + ai * HALF + m * 16;
;                 const float rs = rsv[ai][m];
;                 bf16_t* rowp = H + (size_t)row * ldh + (col0 >> 1);
; #pragma unroll
;                 for (int bj = 0; bj < 2; ++bj) {
;                     const f32x4 v0 = acc[ai][bj][m][0] * rs, v1 = acc[ai][bj][m][1] * rs;
;                     u32x2 w; w.x = cvt_pk_bf16(sg(v0[0], v0[1]), sg(v0[2], v0[3])); w.y = cvt_pk_bf16(sg(v1[0], v1[1]), sg(v1[2], v1[3]));
;                     *(u32x2*)(rowp + bj * (HALF / 2)) = w;
;                 }
;             }
	v_mul_f32_e32 v43, v45, v216
	v_cvt_pk_bf16_f32 v47, v42, v43
	v_mul_f32_e32 v42, 0xbfb8aa3b, v38
	v_exp_f32_e32 v42, v42
	global_store_dwordx2 v[50:51], v[46:47], off
	v_add_f32_e32 v42, 1.0, v42
	v_rcp_f32_e32 v42, v42
	s_nop 0
	v_mul_f32_e32 v38, v38, v42
	v_mul_f32_e32 v38, v39, v38
	v_mul_f32_e32 v39, 0xbfb8aa3b, v40
	v_exp_f32_e32 v39, v39
	s_nop 0
	v_add_f32_e32 v39, 1.0, v39
	v_rcp_f32_e32 v39, v39
	s_nop 0
	v_mul_f32_e32 v39, v40, v39
	v_mul_f32_e32 v39, v41, v39
	v_cvt_pk_bf16_f32 v38, v38, v39
	v_mul_f32_e32 v39, 0xbfb8aa3b, v34
	v_exp_f32_e32 v39, v39
	s_nop 0
	v_add_f32_e32 v39, 1.0, v39
	v_rcp_f32_e32 v39, v39
	s_nop 0
	v_mul_f32_e32 v34, v34, v39
	v_mul_f32_e32 v34, v35, v34
	v_mul_f32_e32 v35, 0xbfb8aa3b, v36
	v_exp_f32_e32 v35, v35
	s_nop 0
	v_add_f32_e32 v35, 1.0, v35
	v_rcp_f32_e32 v35, v35
	s_nop 0
	v_mul_f32_e32 v35, v36, v35
	v_mul_f32_e32 v36, 0xbfb8aa3b, v30
	v_exp_f32_e32 v36, v36
	v_mul_f32_e32 v35, v37, v35
	v_cvt_pk_bf16_f32 v39, v34, v35
	global_store_dwordx2 v[50:51], v[38:39], off offset:128
	v_add_f32_e32 v36, 1.0, v36
	v_rcp_f32_e32 v36, v36
	v_mad_i64_i32 v[34:35], s[24:25], v152, s96, v[132:133]
	v_lshl_add_u64 v[34:35], v[34:35], 0, v[156:157]
	v_mul_f32_e32 v30, v30, v36
	v_mul_f32_e32 v30, v31, v30
	v_mul_f32_e32 v31, 0xbfb8aa3b, v32
	v_exp_f32_e32 v31, v31
	s_nop 0
	v_add_f32_e32 v31, 1.0, v31
	v_rcp_f32_e32 v31, v31
	s_nop 0
	v_mul_f32_e32 v31, v32, v31
	v_mul_f32_e32 v31, v33, v31
	v_cvt_pk_bf16_f32 v30, v30, v31
	v_mul_f32_e32 v31, 0xbfb8aa3b, v26
	v_mul_f32_e32 v216, 0xbfb8aa3b, v28
	v_exp_f32_e32 v31, v31
	v_exp_f32_e32 v216, v216
	v_add_f32_e32 v31, 1.0, v31
	v_add_f32_e32 v216, 1.0, v216
	v_rcp_f32_e32 v31, v31
	v_rcp_f32_e32 v216, v216
	v_mul_f32_e32 v26, v26, v31
	v_mul_f32_e32 v216, v28, v216
	v_mul_f32_e32 v26, v27, v26
	v_mul_f32_e32 v27, v29, v216
	v_cvt_pk_bf16_f32 v31, v26, v27
	v_mul_f32_e32 v26, 0xbfb8aa3b, v22
	v_exp_f32_e32 v26, v26
	global_store_dwordx2 v[34:35], v[30:31], off
	v_add_f32_e32 v26, 1.0, v26
	v_rcp_f32_e32 v26, v26
	s_nop 0
	v_mul_f32_e32 v22, v22, v26
	v_mul_f32_e32 v22, v23, v22
	v_mul_f32_e32 v23, 0xbfb8aa3b, v24
	v_exp_f32_e32 v23, v23
	s_nop 0
	v_add_f32_e32 v23, 1.0, v23
	v_rcp_f32_e32 v23, v23
	s_nop 0
	v_mul_f32_e32 v23, v24, v23
	v_mul_f32_e32 v23, v25, v23
	v_cvt_pk_bf16_f32 v22, v22, v23
	v_mul_f32_e32 v23, 0xbfb8aa3b, v18
	v_exp_f32_e32 v23, v23
	s_nop 0
	v_add_f32_e32 v23, 1.0, v23
	v_rcp_f32_e32 v23, v23
	s_nop 0
	v_mul_f32_e32 v18, v18, v23
	v_mul_f32_e32 v18, v19, v18
	v_mul_f32_e32 v19, 0xbfb8aa3b, v20
	v_exp_f32_e32 v19, v19
	s_nop 0
	v_add_f32_e32 v19, 1.0, v19
	v_rcp_f32_e32 v19, v19
	s_nop 0
	v_mul_f32_e32 v19, v20, v19
	v_mul_f32_e32 v20, 0xbfb8aa3b, v14
	v_exp_f32_e32 v20, v20
	v_mul_f32_e32 v19, v21, v19
	v_cvt_pk_bf16_f32 v23, v18, v19
	global_store_dwordx2 v[34:35], v[22:23], off offset:128
	v_add_f32_e32 v20, 1.0, v20
	v_rcp_f32_e32 v20, v20
	v_mad_i64_i32 v[18:19], s[24:25], v148, s96, v[132:133]
	v_lshl_add_u64 v[18:19], v[18:19], 0, v[156:157]
	v_mul_f32_e32 v14, v14, v20
	v_mul_f32_e32 v14, v15, v14
	v_mul_f32_e32 v15, 0xbfb8aa3b, v16
	v_exp_f32_e32 v15, v15
	s_mov_b64 s[24:25], -1
	v_add_f32_e32 v15, 1.0, v15
	v_rcp_f32_e32 v15, v15
	s_nop 0
	v_mul_f32_e32 v15, v16, v15
	v_mul_f32_e32 v15, v17, v15
	v_cvt_pk_bf16_f32 v14, v14, v15
	v_mul_f32_e32 v15, 0xbfb8aa3b, v10
	v_mul_f32_e32 v216, 0xbfb8aa3b, v12
	v_exp_f32_e32 v15, v15
	v_exp_f32_e32 v216, v216
	v_add_f32_e32 v15, 1.0, v15
	v_add_f32_e32 v216, 1.0, v216
	v_rcp_f32_e32 v15, v15
	v_rcp_f32_e32 v216, v216
	v_mul_f32_e32 v10, v10, v15
	v_mul_f32_e32 v216, v12, v216
	v_mul_f32_e32 v10, v11, v10
	v_mul_f32_e32 v11, v13, v216
	v_cvt_pk_bf16_f32 v15, v10, v11
	v_mul_f32_e32 v10, 0xbfb8aa3b, v6
	v_exp_f32_e32 v10, v10
	global_store_dwordx2 v[18:19], v[14:15], off
	v_add_f32_e32 v10, 1.0, v10
	v_rcp_f32_e32 v10, v10
	s_nop 0
	v_mul_f32_e32 v6, v6, v10
	v_mul_f32_e32 v6, v7, v6
	v_mul_f32_e32 v7, 0xbfb8aa3b, v8
	v_exp_f32_e32 v7, v7
	s_nop 0
	v_add_f32_e32 v7, 1.0, v7
	v_rcp_f32_e32 v7, v7
	s_nop 0
	v_mul_f32_e32 v7, v8, v7
	v_mul_f32_e32 v7, v9, v7
	v_cvt_pk_bf16_f32 v6, v6, v7
	v_mul_f32_e32 v7, 0xbfb8aa3b, v2
	v_mul_f32_e32 v216, 0xbfb8aa3b, v4
	v_exp_f32_e32 v7, v7
	v_exp_f32_e32 v216, v216
	v_add_f32_e32 v7, 1.0, v7
	v_add_f32_e32 v216, 1.0, v216
	v_rcp_f32_e32 v7, v7
	v_rcp_f32_e32 v216, v216
	v_mul_f32_e32 v2, v2, v7
	v_mul_f32_e32 v216, v4, v216
	v_mul_f32_e32 v2, v3, v2
	v_mul_f32_e32 v3, v5, v216
	v_cvt_pk_bf16_f32 v7, v2, v3
	global_store_dwordx2 v[18:19], v[6:7], off offset:128
	s_cbranch_vccnz .LBB0_4832
	s_andn2_b64 vcc, exec, s[14:15]
	s_cbranch_vccnz .LBB0_4831
	s_barrier
	s_branch .LBB0_4831
